# FFN-up GEMMs: next-tile stage-0 LDS-DMA prefetch issued before the epilogue + counted head wait (epilogue stores stay in flight), small per-XCD phase-entry stagger in P8/P10
# speedup vs baseline: 1.0014x; 1.0014x over previous
.LBB0_939:
	s_or_b64 exec, exec, s[38:39]
	s_cmpk_gt_i32 s2, 0x5ff
	s_waitcnt lgkmcnt(0)
	s_barrier
	s_cbranch_scc1 .LBB0_944
	s_lshr_b32 s98, s2, 3
	s_and_b32 s98, s98, 7
	s_cmp_eq_u32 s98, 0
	s_cbranch_scc1 .Lstag_done_p8
.Lstag_loop_p8:
	s_sleep 29
	s_sub_u32 s98, s98, 1
	s_cmp_lg_u32 s98, 0
	s_cbranch_scc1 .Lstag_loop_p8
.Lstag_done_p8:
	s_mov_b32 s101, 0
	s_add_i32 s3, 0, 0x240a8
	v_mov_b32_e32 v133, s3
	s_mov_b64 s[4:5], 0x2400000
	s_mov_b64 s[6:7], 0x1200000
	s_mov_b32 s20, 0x3ffff0
	v_mov_b32_e32 v129, 0
	s_mov_b32 s21, 0xc000
	s_movk_i32 s22, 0xc000
	s_movk_i32 s23, 0x1800
	s_mov_b64 s[8:9], 0x1200080
	s_mov_b64 s[10:11], 0x2400080
	s_add_i32 s24, 0, 0x10000
	s_mov_b32 s25, 0x18000
	s_add_i32 s26, 0, 0x18000
	s_movk_i32 s27, 0x2400
	s_mov_b64 s[12:13], 0x11400000
	s_mov_b32 s28, 0x24000
	s_mov_b32 s29, 0x60000
	s_mov_b32 s30, 0x6c000
	s_mov_b32 s31, 0x78000
	s_mov_b32 s34, 0x84000
	s_mov_b32 s35, 0x90000
	s_mov_b32 s38, 0x9c000
	s_mov_b32 s39, s2
.LBB0_941:
	s_mul_hi_i32 s14, s39, 0x2aaaaaab
	s_lshr_b32 s15, s14, 31
	s_ashr_i32 s14, s14, 5
	s_add_i32 s15, s14, s15
	s_mul_i32 s14, s15, 0xc0
	s_sub_i32 s16, s39, s14
	s_sext_i32_i16 s14, s16
	s_bfe_u32 s14, s14, 0x4001b
	s_add_i32 s14, s16, s14
	s_sext_i32_i16 s17, s14
	s_and_b32 s14, s14, 0xfff0
	s_sub_i32 s14, s16, s14
	s_sext_i32_i16 s19, s14
	s_lshl_b32 s14, s17, 4
	s_and_b32 s14, s14, 0xffffff00
	v_mov_b32_e32 v148, v132
	v_mov_b32_e32 v18, v132
	s_add_i32 s17, s14, 0x500
	ds_read_b64 v[0:1], v133
	s_cmpk_lt_i32 s16, 0x60
	v_lshlrev_b32_e32 v9, 4, v18
	v_and_b32_e32 v8, 32, v18
	v_lshrrev_b32_e32 v10, 1, v18
	v_bitop3_b32 v8, v9, v8, 48 bitop3:0x6c
	s_cselect_b32 s18, s14, s17
	s_lshl_b32 s15, s15, 12
	s_lshl_b32 s16, s19, 8
	v_bfe_u32 v19, v18, 2, 4
	v_and_b32_e32 v20, 32, v10
	v_lshrrev_b32_e32 v21, 1, v8
	v_ashrrev_i32_e32 v22, 3, v18
	s_add_i32 s16, s16, s15
	v_or_b32_e32 v12, v21, v20
	v_and_or_b32 v8, v22, s20, v19
	s_ashr_i32 s17, s16, 31
	v_and_b32_e32 v11, 0xfffffc00, v9
	v_lshl_or_b32 v128, v8, 10, v12
	v_add_u32_e32 v8, 0x2000, v9
	v_add_u32_e32 v10, 0x4000, v9
	v_add_u32_e32 v9, 0x6000, v9
	s_lshl_b64 s[42:43], s[16:17], 11
	s_ashr_i32 s19, s18, 31
	v_ashrrev_i32_e32 v23, 7, v8
	v_ashrrev_i32_e32 v24, 7, v10
	v_ashrrev_i32_e32 v25, 7, v9
	s_waitcnt lgkmcnt(0)
	v_lshl_add_u64 v[2:3], v[0:1], 0, s[42:43]
	s_lshl_b64 s[18:19], s[18:19], 11
	v_and_or_b32 v8, v23, s20, v19
	v_and_or_b32 v10, v24, s20, v19
	v_and_or_b32 v9, v25, s20, v19
	v_add_u32_e32 v149, 0, v11
	v_lshl_add_u64 v[4:5], v[2:3], 0, s[4:5]
	v_lshl_add_u64 v[0:1], v[0:1], 0, s[18:19]
	v_lshl_or_b32 v8, v8, 10, v12
	v_lshl_or_b32 v10, v10, 10, v12
	v_lshl_or_b32 v12, v9, 10, v12
	v_add_u32_e32 v9, 0x8000, v149
	v_lshlrev_b64 v[14:15], 1, v[128:129]
	v_readfirstlane_b32 s15, v149
	v_lshl_add_u64 v[6:7], v[0:1], 0, s[6:7]
	v_lshl_add_u64 v[16:17], v[4:5], 0, v[14:15]
	s_mov_b32 m0, s15
	v_readfirstlane_b32 s15, v9
	v_mov_b32_e32 v9, v129
	v_add_u32_e32 v11, 0x2000, v149
	s_cmp_lg_u32 s101, 0
	s_cbranch_scc1 .Lnxh_942_7
	global_load_lds_dwordx4 v[16:17], off
.Lnxh_942_7:
	v_lshl_add_u64 v[14:15], v[6:7], 0, v[14:15]
	s_mov_b32 m0, s15
	v_lshlrev_b64 v[8:9], 1, v[8:9]
	v_readfirstlane_b32 s15, v11
	v_add_u32_e32 v11, 0xa000, v149
	s_cmp_lg_u32 s101, 0
	s_cbranch_scc1 .Lnxh_942_6
	global_load_lds_dwordx4 v[14:15], off
.Lnxh_942_6:
	v_lshl_add_u64 v[14:15], v[4:5], 0, v[8:9]
	s_mov_b32 m0, s15
	v_readfirstlane_b32 s15, v11
	s_cmp_lg_u32 s101, 0
	s_cbranch_scc1 .Lnxh_942_5
	global_load_lds_dwordx4 v[14:15], off
.Lnxh_942_5:
	v_lshl_add_u64 v[8:9], v[6:7], 0, v[8:9]
	s_mov_b32 m0, s15
	v_mov_b32_e32 v11, v129
	v_add_u32_e32 v13, 0x4000, v149
	s_cmp_lg_u32 s101, 0
	s_cbranch_scc1 .Lnxh_942_4
	global_load_lds_dwordx4 v[8:9], off
.Lnxh_942_4:
	v_lshlrev_b64 v[8:9], 1, v[10:11]
	v_readfirstlane_b32 s15, v13
	v_lshl_add_u64 v[10:11], v[4:5], 0, v[8:9]
	s_mov_b32 m0, s15
	v_lshl_add_u64 v[8:9], v[6:7], 0, v[8:9]
	s_cmp_lg_u32 s101, 0
	s_cbranch_scc1 .Lnxh_942_3
	global_load_lds_dwordx4 v[10:11], off
.Lnxh_942_3:
	v_add_u32_e32 v10, 0xc000, v149
	v_mov_b32_e32 v13, v129
	v_readfirstlane_b32 s15, v10
	s_mov_b32 m0, s15
	v_add_u32_e32 v10, 0x6000, v149
	s_cmp_lg_u32 s101, 0
	s_cbranch_scc1 .Lnxh_942_2
	global_load_lds_dwordx4 v[8:9], off
.Lnxh_942_2:
	v_lshlrev_b64 v[8:9], 1, v[12:13]
	v_readfirstlane_b32 s15, v10
	v_lshl_add_u64 v[4:5], v[4:5], 0, v[8:9]
	s_mov_b32 m0, s15
	v_and_b32_e32 v26, 15, v18
	s_cmp_lg_u32 s101, 0
	s_cbranch_scc1 .Lnxh_942_1
	global_load_lds_dwordx4 v[4:5], off
.Lnxh_942_1:
	v_lshl_add_u64 v[4:5], v[6:7], 0, v[8:9]
	v_add_u32_e32 v6, 0xe000, v149
	v_lshlrev_b32_e32 v10, 10, v19
	v_readfirstlane_b32 s15, v6
	s_mov_b32 m0, s15
	v_lshlrev_b32_e32 v6, 2, v18
	s_cmp_lg_u32 s101, 0
	s_cbranch_scc1 .Lnxh_942_0
	global_load_lds_dwordx4 v[4:5], off
.Lnxh_942_0:
	v_and_b32_e32 v4, 48, v18
	v_lshlrev_b32_e32 v5, 6, v26
	v_and_b32_e32 v6, 32, v6
	v_bitop3_b32 v150, v5, v6, v4 bitop3:0x36
	v_lshlrev_b32_e32 v5, 7, v18
	v_and_b32_e32 v151, 0x6000, v5
	v_lshlrev_b32_e32 v5, 6, v18
	v_and_b32_e32 v152, 0xffffc000, v5
	v_and_b32_e32 v5, 0x3c0, v5
	v_bitop3_b32 v154, v5, v6, v4 bitop3:0x36
	v_lshlrev_b32_e32 v4, 10, v25
	v_and_or_b32 v4, v4, s22, v21
	v_lshlrev_b32_e32 v6, 10, v24
	v_or3_b32 v128, v4, v10, v20
	v_and_or_b32 v6, v6, s22, v21
	v_lshlrev_b32_e32 v8, 10, v23
	v_lshlrev_b64 v[4:5], 1, v[128:129]
	v_or3_b32 v128, v6, v10, v20
	v_and_or_b32 v8, v8, s22, v21
	v_lshlrev_b32_e32 v11, 10, v22
	v_lshlrev_b64 v[6:7], 1, v[128:129]
	v_or3_b32 v128, v8, v10, v20
	v_and_or_b32 v11, v11, s22, v21
	v_lshlrev_b64 v[8:9], 1, v[128:129]
	v_or3_b32 v128, v11, v10, v20
	s_nop 0
	v_lshl_add_u64 v[0:1], v[0:1], 0, s[8:9]
	v_lshlrev_b64 v[10:11], 1, v[128:129]
	v_lshl_add_u64 v[130:131], v[0:1], 0, v[4:5]
	v_lshl_add_u64 v[134:135], v[0:1], 0, v[6:7]
	v_lshl_add_u64 v[136:137], v[0:1], 0, v[8:9]
	v_lshl_add_u64 v[138:139], v[0:1], 0, v[10:11]
	v_lshl_add_u64 v[0:1], v[2:3], 0, s[10:11]
	v_or_b32_e32 v153, 0x800, v152
	v_or_b32_e32 v155, 0x1000, v152
	v_or_b32_e32 v156, 0x1800, v152
	v_or_b32_e32 v157, 0x2000, v152
	v_or_b32_e32 v158, 0x2800, v152
	v_or_b32_e32 v159, 0x3000, v152
	v_or_b32_e32 v160, 0x3800, v152
	v_lshl_add_u64 v[140:141], v[0:1], 0, v[4:5]
	v_lshl_add_u64 v[142:143], v[0:1], 0, v[6:7]
	v_lshl_add_u64 v[144:145], v[0:1], 0, v[8:9]
	v_lshl_add_u64 v[146:147], v[0:1], 0, v[10:11]
	s_mov_b64 s[18:19], 0
	s_mov_b32 s15, 0
	v_mov_b32_e32 v0, 0
	v_mov_b32_e32 v1, v129
	v_mov_b32_e32 v2, v129
	v_mov_b32_e32 v3, v129
	v_mov_b32_e32 v4, 0
	v_mov_b32_e32 v5, v129
	v_mov_b32_e32 v6, v129
	v_mov_b32_e32 v7, v129
	v_mov_b32_e32 v8, 0
	v_mov_b32_e32 v9, v129
	v_mov_b32_e32 v10, v129
	v_mov_b32_e32 v11, v129
	v_mov_b32_e32 v12, 0
	v_mov_b32_e32 v14, v129
	v_mov_b32_e32 v15, v129
	v_mov_b32_e32 v16, 0
	v_mov_b32_e32 v17, v129
	v_mov_b32_e32 v18, v129
	v_mov_b32_e32 v19, v129
	v_mov_b32_e32 v20, 0
	v_mov_b32_e32 v21, v129
	v_mov_b32_e32 v22, v129
	v_mov_b32_e32 v23, v129
	v_mov_b32_e32 v24, 0
	v_mov_b32_e32 v25, v129
	v_mov_b32_e32 v26, v129
	v_mov_b32_e32 v27, v129
	v_mov_b32_e32 v28, 0
	v_mov_b32_e32 v29, v129
	v_mov_b32_e32 v30, v129
	v_mov_b32_e32 v31, v129
	v_mov_b32_e32 v32, 0
	v_mov_b32_e32 v33, v129
	v_mov_b32_e32 v34, v129
	v_mov_b32_e32 v35, v129
	v_mov_b32_e32 v36, 0
	v_mov_b32_e32 v37, v129
	v_mov_b32_e32 v38, v129
	v_mov_b32_e32 v39, v129
	v_mov_b32_e32 v40, 0
	v_mov_b32_e32 v41, v129
	v_mov_b32_e32 v42, v129
	v_mov_b32_e32 v43, v129
	v_mov_b32_e32 v44, 0
	v_mov_b32_e32 v45, v129
	v_mov_b32_e32 v46, v129
	v_mov_b32_e32 v47, v129
	v_mov_b32_e32 v48, 0
	v_mov_b32_e32 v49, v129
	v_mov_b32_e32 v50, v129
	v_mov_b32_e32 v51, v129
	v_mov_b32_e32 v52, 0
	v_mov_b32_e32 v53, v129
	v_mov_b32_e32 v54, v129
	v_mov_b32_e32 v55, v129
	v_mov_b32_e32 v56, 0
	v_mov_b32_e32 v57, v129
	v_mov_b32_e32 v58, v129
	v_mov_b32_e32 v59, v129
	v_mov_b32_e32 v60, 0
	v_mov_b32_e32 v61, v129
	v_mov_b32_e32 v62, v129
	v_mov_b32_e32 v63, v129
	v_mov_b32_e32 v64, 0
	v_mov_b32_e32 v65, v129
	v_mov_b32_e32 v66, v129
	v_mov_b32_e32 v67, v129
	v_mov_b32_e32 v68, 0
	v_mov_b32_e32 v69, v129
	v_mov_b32_e32 v70, v129
	v_mov_b32_e32 v71, v129
	v_mov_b32_e32 v72, 0
	v_mov_b32_e32 v73, v129
	v_mov_b32_e32 v74, v129
	v_mov_b32_e32 v75, v129
	v_mov_b32_e32 v76, 0
	v_mov_b32_e32 v77, v129
	v_mov_b32_e32 v78, v129
	v_mov_b32_e32 v79, v129
	v_mov_b32_e32 v80, 0
	v_mov_b32_e32 v81, v129
	v_mov_b32_e32 v82, v129
	v_mov_b32_e32 v83, v129
	v_mov_b32_e32 v84, 0
	v_mov_b32_e32 v85, v129
	v_mov_b32_e32 v86, v129
	v_mov_b32_e32 v87, v129
	v_mov_b32_e32 v88, 0
	v_mov_b32_e32 v89, v129
	v_mov_b32_e32 v90, v129
	v_mov_b32_e32 v91, v129
	v_mov_b32_e32 v92, 0
	v_mov_b32_e32 v93, v129
	v_mov_b32_e32 v94, v129
	v_mov_b32_e32 v95, v129
	v_mov_b32_e32 v96, 0
	v_mov_b32_e32 v97, v129
	v_mov_b32_e32 v98, v129
	v_mov_b32_e32 v99, v129
	v_mov_b32_e32 v100, 0
	v_mov_b32_e32 v101, v129
	v_mov_b32_e32 v102, v129
	v_mov_b32_e32 v103, v129
	v_mov_b32_e32 v104, 0
	v_mov_b32_e32 v105, v129
	v_mov_b32_e32 v106, v129
	v_mov_b32_e32 v107, v129
	v_mov_b32_e32 v108, 0
	v_mov_b32_e32 v109, v129
	v_mov_b32_e32 v110, v129
	v_mov_b32_e32 v111, v129
	v_mov_b32_e32 v112, 0
	v_mov_b32_e32 v113, v129
	v_mov_b32_e32 v114, v129
	v_mov_b32_e32 v115, v129
	v_mov_b32_e32 v116, 0
	v_mov_b32_e32 v117, v129
	v_mov_b32_e32 v118, v129
	v_mov_b32_e32 v119, v129
	v_mov_b32_e32 v120, 0
	v_mov_b32_e32 v121, v129
	v_mov_b32_e32 v122, v129
	v_mov_b32_e32 v123, v129
	v_mov_b32_e32 v124, 0
	v_mov_b32_e32 v125, v129
	v_mov_b32_e32 v126, v129
	v_mov_b32_e32 v127, v129
	s_cmp_lg_u32 s101, 0
	s_cbranch_scc1 .Lnxw_942
	s_waitcnt vmcnt(0)
.Lnxw_942:
	s_waitcnt vmcnt(16) lgkmcnt(0)
	s_barrier
	v_readfirstlane_b32 s100, v149
	s_mov_b64 s[98:99], 0x80
	s_and_b32 s17, s15, 0x10000
	s_xor_b32 s42, s17, 0x10000
	s_add_i32 s17, s17, 0
	v_add3_u32 v128, s17, v150, v151
	v_add3_u32 v161, s17, v150, v152
	v_add3_u32 v194, s17, v154, v153
	v_add3_u32 v195, s17, v154, v155
	v_add3_u32 v196, s17, v154, v156
	v_add3_u32 v197, s17, v154, v157
	v_add3_u32 v198, s17, v154, v158
	v_add3_u32 v199, s17, v154, v159
	v_add3_u32 v200, s17, v154, v160
	ds_read_b128 v[178:181], v128 offset:32768
	ds_read_b128 v[162:165], v161
	ds_read_b128 v[166:169], v194
	ds_read_b128 v[170:173], v195
	ds_read_b128 v[174:177], v196
	ds_read_b128 v[182:185], v128 offset:34816
	ds_read_b128 v[186:189], v128 offset:36864
	ds_read_b128 v[190:193], v128 offset:38912
	s_add_i32 s101, s100, s42
	s_mov_b32 m0, s101
	s_nop 0
	global_load_lds_dwordx4 v[146:147], off
	s_add_i32 m0, s101, 0x8000
	s_nop 0
	global_load_lds_dwordx4 v[138:139], off
	s_add_i32 m0, s101, 0x2000
	s_nop 0
	global_load_lds_dwordx4 v[144:145], off
	s_add_i32 m0, s101, 0xa000
	s_nop 0
	global_load_lds_dwordx4 v[136:137], off
	s_add_i32 m0, s101, 0x4000
	s_nop 0
	global_load_lds_dwordx4 v[142:143], off
	s_add_i32 m0, s101, 0xc000
	s_nop 0
	global_load_lds_dwordx4 v[134:135], off
	s_add_i32 m0, s101, 0x6000
	s_nop 0
	global_load_lds_dwordx4 v[140:141], off
	s_add_i32 m0, s101, 0xe000
	s_nop 0
	global_load_lds_dwordx4 v[130:131], off

.Lex_942:
	s_mov_b32 s101, 0
	s_cmpk_lg_i32 s40, 0x100
	s_cbranch_scc1 .Lnxn_942
	s_add_i32 s98, s39, s40
	s_cmpk_gt_i32 s98, 0x5ff
	s_cbranch_scc1 .Lnxn_942
	s_mul_hi_u32 s98, s39, 0x2aaaaaab
	s_lshr_b32 s98, s98, 5
	s_mul_i32 s98, s98, 0xc0
	s_sub_i32 s98, s39, s98
	s_lshr_b32 s98, s98, 4
	s_mov_b32 vcc_lo, 0
	s_mov_b32 s99, 0
	s_cmpk_lg_u32 s98, 0
	s_cbranch_scc1 .Lnxj_942_0
	s_mov_b32 vcc_lo, 0x1ff880
	s_mov_b32 s99, 0x7ff880
.Lnxj_942_0:
	s_cmpk_lg_u32 s98, 1
	s_cbranch_scc1 .Lnxj_942_1
	s_mov_b32 vcc_lo, 0x1ff880
	s_mov_b32 s99, 0x7ff880
.Lnxj_942_1:
	s_cmpk_lg_u32 s98, 2
	s_cbranch_scc1 .Lnxj_942_2
	s_mov_b32 vcc_lo, 0x47f880
	s_mov_b32 s99, 0x7ff880
.Lnxj_942_2:
	s_cmpk_lg_u32 s98, 3
	s_cbranch_scc1 .Lnxj_942_3
	s_mov_b32 vcc_lo, 0x47f880
	s_mov_b32 s99, 0x7ff880
.Lnxj_942_3:
	s_cmpk_lg_u32 s98, 4
	s_cbranch_scc1 .Lnxj_942_4
	s_mov_b32 vcc_lo, 0x47f880
	s_mov_b32 s99, 0x7ff880
.Lnxj_942_4:
	s_cmpk_lg_u32 s98, 5
	s_cbranch_scc1 .Lnxj_942_5
	s_mov_b32 vcc_lo, 0x47f880
	s_mov_b32 s99, 0x7ff880
.Lnxj_942_5:
	s_cmpk_lg_u32 s98, 6
	s_cbranch_scc1 .Lnxj_942_6
	s_mov_b32 vcc_lo, 0x1ff880
	s_mov_b32 s99, 0x7ff880
.Lnxj_942_6:
	s_cmpk_lg_u32 s98, 7
	s_cbranch_scc1 .Lnxj_942_7
	s_mov_b32 vcc_lo, 0x1ff880
	s_mov_b32 s99, 0x7ff880
.Lnxj_942_7:
	s_cmpk_lg_u32 s98, 8
	s_cbranch_scc1 .Lnxj_942_8
	s_mov_b32 vcc_lo, 0xff97f880
	s_mov_b32 s99, 0xfff880
.Lnxj_942_8:
	s_cmpk_lg_u32 s98, 9
	s_cbranch_scc1 .Lnxj_942_9
	s_mov_b32 vcc_lo, 0xff97f880
	s_mov_b32 s99, 0xfff880
.Lnxj_942_9:
	s_cmpk_lg_u32 s98, 10
	s_cbranch_scc1 .Lnxj_942_10
	s_mov_b32 vcc_lo, 0xff97f880
	s_mov_b32 s99, 0xfff880
.Lnxj_942_10:
	s_cmpk_lg_u32 s98, 11
	s_cbranch_scc1 .Lnxj_942_11
	s_mov_b32 vcc_lo, 0xff97f880
	s_mov_b32 s99, 0xfff880
.Lnxj_942_11:
	s_ashr_i32 vcc_hi, vcc_lo, 31
	s_mov_b32 s98, s99
	s_mov_b32 s99, 0
	s_mov_b32 m0, s100
	v_lshl_add_u64 v[240:241], v[146:147], 0, s[98:99]
	global_load_lds_dwordx4 v[240:241], off
	s_add_i32 m0, s100, 0x8000
	v_lshl_add_u64 v[240:241], v[138:139], 0, vcc
	global_load_lds_dwordx4 v[240:241], off
	s_add_i32 m0, s100, 0x2000
	v_lshl_add_u64 v[240:241], v[144:145], 0, s[98:99]
	global_load_lds_dwordx4 v[240:241], off
	s_add_i32 m0, s100, 0xa000
	v_lshl_add_u64 v[240:241], v[136:137], 0, vcc
	global_load_lds_dwordx4 v[240:241], off
	s_add_i32 m0, s100, 0x4000
	v_lshl_add_u64 v[240:241], v[142:143], 0, s[98:99]
	global_load_lds_dwordx4 v[240:241], off
	s_add_i32 m0, s100, 0xc000
	v_lshl_add_u64 v[240:241], v[134:135], 0, vcc
	global_load_lds_dwordx4 v[240:241], off
	s_add_i32 m0, s100, 0x6000
	v_lshl_add_u64 v[240:241], v[140:141], 0, s[98:99]
	global_load_lds_dwordx4 v[240:241], off
	s_add_i32 m0, s100, 0xe000
	v_lshl_add_u64 v[240:241], v[130:131], 0, vcc
	global_load_lds_dwordx4 v[240:241], off
	s_mov_b32 s101, 1
.Lnxn_942:
	s_waitcnt lgkmcnt(0)
	v_add3_u32 v128, s24, v154, v160
	v_add3_u32 v130, s24, v154, v159
	v_add3_u32 v131, s24, v154, v158
	v_add3_u32 v146, s24, v154, v157
	v_add3_u32 v147, s24, v154, v156
	v_add3_u32 v149, s24, v154, v155
	v_add3_u32 v186, s24, v154, v153
	v_add3_u32 v187, s24, v150, v152
	v_add3_u32 v188, s26, v150, v151
	ds_read_b128 v[134:137], v128
	ds_read_b128 v[138:141], v130
	ds_read_b128 v[142:145], v131
	ds_read_b128 v[158:161], v146
	ds_read_b128 v[162:165], v147
	ds_read_b128 v[166:169], v149
	ds_read_b128 v[154:157], v186
	ds_read_b128 v[170:173], v187
	ds_read_b128 v[178:181], v188 offset:4096
	s_waitcnt lgkmcnt(0)
	v_mfma_f32_16x16x32_bf16 v[4:7], v[178:181], v[138:141], v[4:7]
	ds_read_b128 v[174:177], v188 offset:2048
	s_waitcnt lgkmcnt(0)
	v_mfma_f32_16x16x32_bf16 v[8:11], v[174:177], v[138:141], v[8:11]
	ds_read_b128 v[150:153], v188
	s_waitcnt lgkmcnt(0)
	v_mfma_f32_16x16x32_bf16 v[12:15], v[150:153], v[138:141], v[12:15]
	v_mfma_f32_16x16x32_bf16 v[112:115], v[150:153], v[134:137], v[112:115]
	v_mfma_f32_16x16x32_bf16 v[108:111], v[150:153], v[170:173], v[108:111]
	v_mfma_f32_16x16x32_bf16 v[92:95], v[150:153], v[154:157], v[92:95]
	v_mfma_f32_16x16x32_bf16 v[76:79], v[150:153], v[166:169], v[76:79]
	v_mfma_f32_16x16x32_bf16 v[116:119], v[174:177], v[134:137], v[116:119]
	v_mfma_f32_16x16x32_bf16 v[104:107], v[174:177], v[170:173], v[104:107]
	v_mfma_f32_16x16x32_bf16 v[88:91], v[174:177], v[154:157], v[88:91]
	v_mfma_f32_16x16x32_bf16 v[72:75], v[174:177], v[166:169], v[72:75]
	v_mfma_f32_16x16x32_bf16 v[120:123], v[178:181], v[134:137], v[120:123]
	v_mfma_f32_16x16x32_bf16 v[100:103], v[178:181], v[170:173], v[100:103]
	v_mfma_f32_16x16x32_bf16 v[84:87], v[178:181], v[154:157], v[84:87]
	v_mfma_f32_16x16x32_bf16 v[68:71], v[178:181], v[166:169], v[68:71]
	ds_read_b128 v[182:185], v188 offset:6144
	s_waitcnt lgkmcnt(0)
	v_mfma_f32_16x16x32_bf16 v[124:127], v[182:185], v[134:137], v[124:127]
	v_mfma_f32_16x16x32_bf16 v[96:99], v[182:185], v[170:173], v[96:99]
	v_mfma_f32_16x16x32_bf16 v[80:83], v[182:185], v[154:157], v[80:83]
	v_mfma_f32_16x16x32_bf16 v[64:67], v[182:185], v[166:169], v[64:67]
	v_mfma_f32_16x16x32_bf16 v[48:51], v[182:185], v[162:165], v[48:51]
	v_mfma_f32_16x16x32_bf16 v[52:55], v[178:181], v[162:165], v[52:55]
	v_mfma_f32_16x16x32_bf16 v[56:59], v[174:177], v[162:165], v[56:59]
	v_mfma_f32_16x16x32_bf16 v[60:63], v[150:153], v[162:165], v[60:63]
	v_mfma_f32_16x16x32_bf16 v[44:47], v[150:153], v[158:161], v[44:47]
	v_mfma_f32_16x16x32_bf16 v[40:43], v[174:177], v[158:161], v[40:43]
	v_mfma_f32_16x16x32_bf16 v[36:39], v[178:181], v[158:161], v[36:39]
	v_mfma_f32_16x16x32_bf16 v[32:35], v[182:185], v[158:161], v[32:35]
	v_mfma_f32_16x16x32_bf16 v[28:31], v[150:153], v[142:145], v[28:31]
	v_mfma_f32_16x16x32_bf16 v[24:27], v[174:177], v[142:145], v[24:27]
	v_mfma_f32_16x16x32_bf16 v[20:23], v[178:181], v[142:145], v[20:23]
	v_mfma_f32_16x16x32_bf16 v[16:19], v[182:185], v[142:145], v[16:19]
	v_mfma_f32_16x16x32_bf16 v[0:3], v[182:185], v[138:141], v[0:3]
	ds_read_b128 v[134:137], v188 offset:1024
	ds_read_b128 v[138:141], v188 offset:3072
	ds_read_b128 v[142:145], v188 offset:5120
	ds_read_b128 v[154:157], v188 offset:7168
	ds_read_b128 v[150:153], v187 offset:1024
	ds_read_b128 v[158:161], v186 offset:1024
	ds_read_b128 v[162:165], v149 offset:1024
	ds_read_b128 v[166:169], v147 offset:1024
	s_waitcnt lgkmcnt(3)
	v_mfma_f32_16x16x32_bf16 v[108:111], v[134:137], v[150:153], v[108:111]
	v_mfma_f32_16x16x32_bf16 v[104:107], v[138:141], v[150:153], v[104:107]
	v_mfma_f32_16x16x32_bf16 v[100:103], v[142:145], v[150:153], v[100:103]
	v_mfma_f32_16x16x32_bf16 v[96:99], v[154:157], v[150:153], v[96:99]
	ds_read_b128 v[150:153], v146 offset:1024
	s_waitcnt lgkmcnt(3)
	v_mfma_f32_16x16x32_bf16 v[92:95], v[134:137], v[158:161], v[92:95]
	v_mfma_f32_16x16x32_bf16 v[88:91], v[138:141], v[158:161], v[88:91]
	v_mfma_f32_16x16x32_bf16 v[84:87], v[142:145], v[158:161], v[84:87]
	v_mfma_f32_16x16x32_bf16 v[80:83], v[154:157], v[158:161], v[80:83]
	ds_read_b128 v[158:161], v131 offset:1024
	s_waitcnt lgkmcnt(3)
	v_mfma_f32_16x16x32_bf16 v[76:79], v[134:137], v[162:165], v[76:79]
	v_mfma_f32_16x16x32_bf16 v[72:75], v[138:141], v[162:165], v[72:75]
	v_mfma_f32_16x16x32_bf16 v[68:71], v[142:145], v[162:165], v[68:71]
	v_mfma_f32_16x16x32_bf16 v[64:67], v[154:157], v[162:165], v[64:67]
	ds_read_b128 v[162:165], v130 offset:1024
	s_waitcnt lgkmcnt(3)
	v_mfma_f32_16x16x32_bf16 v[60:63], v[134:137], v[166:169], v[60:63]
	v_mfma_f32_16x16x32_bf16 v[56:59], v[138:141], v[166:169], v[56:59]
	v_mfma_f32_16x16x32_bf16 v[52:55], v[142:145], v[166:169], v[52:55]
	v_mfma_f32_16x16x32_bf16 v[48:51], v[154:157], v[166:169], v[48:51]
	ds_read_b128 v[166:169], v128 offset:1024
	s_waitcnt lgkmcnt(3)
	v_mfma_f32_16x16x32_bf16 v[44:47], v[134:137], v[150:153], v[44:47]
	v_mfma_f32_16x16x32_bf16 v[40:43], v[138:141], v[150:153], v[40:43]
	v_mfma_f32_16x16x32_bf16 v[36:39], v[142:145], v[150:153], v[36:39]
	v_mfma_f32_16x16x32_bf16 v[32:35], v[154:157], v[150:153], v[32:35]
	s_waitcnt lgkmcnt(2)
	v_mfma_f32_16x16x32_bf16 v[28:31], v[134:137], v[158:161], v[28:31]
	v_mfma_f32_16x16x32_bf16 v[24:27], v[138:141], v[158:161], v[24:27]
	v_mfma_f32_16x16x32_bf16 v[20:23], v[142:145], v[158:161], v[20:23]
	v_mfma_f32_16x16x32_bf16 v[16:19], v[154:157], v[158:161], v[16:19]
	s_waitcnt lgkmcnt(1)
	v_mfma_f32_16x16x32_bf16 v[12:15], v[134:137], v[162:165], v[12:15]
	v_mfma_f32_16x16x32_bf16 v[8:11], v[138:141], v[162:165], v[8:11]
	v_mfma_f32_16x16x32_bf16 v[4:7], v[142:145], v[162:165], v[4:7]
	v_mfma_f32_16x16x32_bf16 v[0:3], v[154:157], v[162:165], v[0:3]
	s_waitcnt lgkmcnt(0)
	v_mfma_f32_16x16x32_bf16 v[112:115], v[134:137], v[166:169], v[112:115]
	v_mfma_f32_16x16x32_bf16 v[116:119], v[138:141], v[166:169], v[116:119]
	v_mfma_f32_16x16x32_bf16 v[120:123], v[142:145], v[166:169], v[120:123]
	v_mfma_f32_16x16x32_bf16 v[124:127], v[154:157], v[166:169], v[124:127]
	v_mov_b32_e32 v128, s3
	s_waitcnt vmcnt(8)
	s_barrier
	ds_read_b64 v[130:131], v128
	v_ashrrev_i32_e32 v128, 1, v148
	v_and_b32_e32 v128, 0xffffff80, v128
	v_add_u32_e32 v128, s16, v128
	s_ashr_i32 s15, s14, 31
	s_waitcnt lgkmcnt(0)
	v_mad_i64_i32 v[130:131], s[16:17], v128, s23, v[130:131]
	v_and_b32_e32 v128, 0xc0, v148
	v_lshrrev_b32_e32 v135, 6, v148
	v_lshl_add_u64 v[130:131], s[14:15], 1, v[130:131]
	v_lshlrev_b32_e32 v128, 1, v128
	v_lshl_add_u64 v[130:131], v[130:131], 0, v[128:129]
	v_mul_lo_u32 v128, v135, s27
	v_add_u32_e32 v135, s24, v128
	v_lshrrev_b32_e32 v128, 1, v148
	v_and_b32_e32 v136, 24, v128
	v_lshlrev_b32_e32 v128, 4, v148
	v_bfe_u32 v137, v148, 3, 3
	v_and_b32_e32 v134, 15, v148
	v_and_b32_e32 v128, 0x70, v128
	v_mul_u32_u24_e32 v138, 0x90, v137
	v_lshl_add_u64 v[130:131], v[130:131], 0, v[128:129]
	v_add3_u32 v138, v135, v128, v138
	v_mul_u32_u24_e32 v128, 0x90, v134
	v_add3_u32 v134, v135, v136, v128
	v_cvt_pk_bf16_f32 v108, v108, v109
	v_cvt_pk_bf16_f32 v109, v110, v111
	v_cvt_pk_bf16_f32 v104, v104, v105
	v_cvt_pk_bf16_f32 v105, v106, v107
	v_cvt_pk_bf16_f32 v100, v100, v101
	v_cvt_pk_bf16_f32 v101, v102, v103
	v_cvt_pk_bf16_f32 v96, v96, v97
	v_cvt_pk_bf16_f32 v97, v98, v99
	v_cvt_pk_bf16_f32 v92, v92, v93
	v_cvt_pk_bf16_f32 v93, v94, v95
	v_cvt_pk_bf16_f32 v88, v88, v89
	v_cvt_pk_bf16_f32 v89, v90, v91
	v_cvt_pk_bf16_f32 v84, v84, v85
	v_cvt_pk_bf16_f32 v85, v86, v87
	v_cvt_pk_bf16_f32 v80, v80, v81
	v_cvt_pk_bf16_f32 v81, v82, v83
	v_cvt_pk_bf16_f32 v76, v76, v77
	v_cvt_pk_bf16_f32 v77, v78, v79
	v_cvt_pk_bf16_f32 v72, v72, v73
	v_cvt_pk_bf16_f32 v73, v74, v75
	v_cvt_pk_bf16_f32 v68, v68, v69
	v_cvt_pk_bf16_f32 v69, v70, v71
	v_cvt_pk_bf16_f32 v64, v64, v65
	v_cvt_pk_bf16_f32 v65, v66, v67
	v_cvt_pk_bf16_f32 v60, v60, v61
	v_cvt_pk_bf16_f32 v61, v62, v63
	v_cvt_pk_bf16_f32 v56, v56, v57
	v_cvt_pk_bf16_f32 v57, v58, v59
	v_cvt_pk_bf16_f32 v52, v52, v53
	v_cvt_pk_bf16_f32 v53, v54, v55
	v_cvt_pk_bf16_f32 v48, v48, v49
	v_cvt_pk_bf16_f32 v49, v50, v51
	ds_write_b64 v134, v[108:109]
	ds_write_b64 v134, v[104:105] offset:32
	ds_write_b64 v134, v[100:101] offset:64
	ds_write_b64 v134, v[96:97] offset:96
	ds_write_b64 v134, v[92:93] offset:2304
	ds_write_b64 v134, v[88:89] offset:2336
	ds_write_b64 v134, v[84:85] offset:2368
	ds_write_b64 v134, v[80:81] offset:2400
	ds_write_b64 v134, v[76:77] offset:4608
	ds_write_b64 v134, v[72:73] offset:4640
	ds_write_b64 v134, v[68:69] offset:4672
	ds_write_b64 v134, v[64:65] offset:4704
	ds_write_b64 v134, v[60:61] offset:6912
	ds_write_b64 v134, v[56:57] offset:6944
	ds_write_b64 v134, v[52:53] offset:6976
	ds_write_b64 v134, v[48:49] offset:7008
	ds_read_b128 v[48:51], v138
	v_mul_u32_u24_e32 v54, 0xc00, v137
	v_lshl_add_u64 v[52:53], v[130:131], 0, s[12:13]
	v_lshlrev_b32_e32 v128, 1, v54
	v_lshl_add_u64 v[54:55], v[52:53], 0, v[128:129]
	s_waitcnt lgkmcnt(0)
	global_store_dwordx4 v[54:55], v[48:51], off nt
	ds_read_b128 v[48:51], v138 offset:1152
	v_add_co_u32_e32 v56, vcc, s21, v54
	v_cvt_pk_bf16_f32 v0, v0, v1
	s_nop 0
	v_addc_co_u32_e32 v57, vcc, 0, v55, vcc
	s_waitcnt lgkmcnt(0)
	global_store_dwordx4 v[56:57], v[48:51], off nt
	ds_read_b128 v[48:51], v138 offset:2304
	v_add_co_u32_e32 v56, vcc, s25, v54
	v_cvt_pk_bf16_f32 v1, v2, v3
	s_nop 0
	v_addc_co_u32_e32 v57, vcc, 0, v55, vcc
	s_waitcnt lgkmcnt(0)
	global_store_dwordx4 v[56:57], v[48:51], off nt
	ds_read_b128 v[48:51], v138 offset:3456
	v_add_co_u32_e32 v56, vcc, s28, v54
	v_cvt_pk_bf16_f32 v44, v44, v45
	s_nop 0
	v_addc_co_u32_e32 v57, vcc, 0, v55, vcc
	s_waitcnt lgkmcnt(0)
	global_store_dwordx4 v[56:57], v[48:51], off nt
	ds_read_b128 v[48:51], v138 offset:4608
	v_or_b32_e32 v56, 0x30000, v128
	v_mov_b32_e32 v57, v129
	v_lshl_add_u64 v[56:57], v[52:53], 0, v[56:57]
	v_cvt_pk_bf16_f32 v45, v46, v47
	s_waitcnt lgkmcnt(0)
	global_store_dwordx4 v[56:57], v[48:51], off nt
	ds_read_b128 v[48:51], v138 offset:5760
	v_add_u32_e32 v56, 0x3c000, v128
	v_mov_b32_e32 v57, v129
	v_lshl_add_u64 v[56:57], v[52:53], 0, v[56:57]
	v_cvt_pk_bf16_f32 v40, v40, v41
	s_waitcnt lgkmcnt(0)
	global_store_dwordx4 v[56:57], v[48:51], off nt
	ds_read_b128 v[48:51], v138 offset:6912
	v_add_u32_e32 v56, 0x48000, v128
	v_mov_b32_e32 v57, v129
	v_lshl_add_u64 v[56:57], v[52:53], 0, v[56:57]
	v_add_u32_e32 v128, 0x54000, v128
	s_waitcnt lgkmcnt(0)
	global_store_dwordx4 v[56:57], v[48:51], off nt
	ds_read_b128 v[48:51], v138 offset:8064
	v_lshl_add_u64 v[52:53], v[52:53], 0, v[128:129]
	v_cvt_pk_bf16_f32 v41, v42, v43
	v_cvt_pk_bf16_f32 v36, v36, v37
	v_cvt_pk_bf16_f32 v37, v38, v39
	s_waitcnt lgkmcnt(0)
	global_store_dwordx4 v[52:53], v[48:51], off nt
	ds_write_b64 v134, v[0:1] offset:4704
	v_cvt_pk_bf16_f32 v0, v112, v113
	v_cvt_pk_bf16_f32 v1, v114, v115
	ds_write_b64 v134, v[0:1] offset:6912
	v_cvt_pk_bf16_f32 v0, v116, v117
	v_cvt_pk_bf16_f32 v1, v118, v119
	ds_write_b64 v134, v[0:1] offset:6944
	v_cvt_pk_bf16_f32 v0, v120, v121
	v_cvt_pk_bf16_f32 v1, v122, v123
	v_cvt_pk_bf16_f32 v32, v32, v33
	v_cvt_pk_bf16_f32 v33, v34, v35
	v_cvt_pk_bf16_f32 v28, v28, v29
	v_cvt_pk_bf16_f32 v29, v30, v31
	v_cvt_pk_bf16_f32 v24, v24, v25
	v_cvt_pk_bf16_f32 v25, v26, v27
	v_cvt_pk_bf16_f32 v20, v20, v21
	v_cvt_pk_bf16_f32 v21, v22, v23
	v_cvt_pk_bf16_f32 v16, v16, v17
	v_cvt_pk_bf16_f32 v17, v18, v19
	v_cvt_pk_bf16_f32 v12, v12, v13
	v_cvt_pk_bf16_f32 v13, v14, v15
	v_cvt_pk_bf16_f32 v8, v8, v9
	v_cvt_pk_bf16_f32 v9, v10, v11
	v_cvt_pk_bf16_f32 v4, v4, v5
	v_cvt_pk_bf16_f32 v5, v6, v7
	ds_write_b64 v134, v[0:1] offset:6976
	v_cvt_pk_bf16_f32 v0, v124, v125
	v_cvt_pk_bf16_f32 v1, v126, v127
	ds_write_b64 v134, v[44:45]
	ds_write_b64 v134, v[40:41] offset:32
	ds_write_b64 v134, v[36:37] offset:64
	ds_write_b64 v134, v[32:33] offset:96
	ds_write_b64 v134, v[28:29] offset:2304
	ds_write_b64 v134, v[24:25] offset:2336
	ds_write_b64 v134, v[20:21] offset:2368
	ds_write_b64 v134, v[16:17] offset:2400
	ds_write_b64 v134, v[12:13] offset:4608
	ds_write_b64 v134, v[8:9] offset:4640
	ds_write_b64 v134, v[4:5] offset:4672
	ds_write_b64 v134, v[0:1] offset:7008
	ds_read_b128 v[0:3], v138
	v_add_co_u32_e32 v4, vcc, s29, v54
	s_add_i32 s39, s39, s40
	s_nop 0
	v_addc_co_u32_e32 v5, vcc, 0, v55, vcc
	s_waitcnt lgkmcnt(0)
	global_store_dwordx4 v[4:5], v[0:3], off nt
	ds_read_b128 v[0:3], v138 offset:1152
	v_add_co_u32_e32 v4, vcc, s30, v54
	s_cmpk_gt_i32 s39, 0x5ff
	s_nop 0
	v_addc_co_u32_e32 v5, vcc, 0, v55, vcc
	s_waitcnt lgkmcnt(0)
	global_store_dwordx4 v[4:5], v[0:3], off nt
	ds_read_b128 v[0:3], v138 offset:2304
	v_add_co_u32_e32 v4, vcc, s31, v54
	s_nop 1
	v_addc_co_u32_e32 v5, vcc, 0, v55, vcc
	s_waitcnt lgkmcnt(0)
	global_store_dwordx4 v[4:5], v[0:3], off nt
	ds_read_b128 v[0:3], v138 offset:3456
	v_add_co_u32_e32 v4, vcc, s34, v54
	s_nop 1
	v_addc_co_u32_e32 v5, vcc, 0, v55, vcc
	s_waitcnt lgkmcnt(0)
	global_store_dwordx4 v[4:5], v[0:3], off nt
	ds_read_b128 v[0:3], v138 offset:4608
	v_add_co_u32_e32 v4, vcc, s35, v54
	s_nop 1
	v_addc_co_u32_e32 v5, vcc, 0, v55, vcc
	s_waitcnt lgkmcnt(0)
	global_store_dwordx4 v[4:5], v[0:3], off nt
	ds_read_b128 v[0:3], v138 offset:5760
	v_add_co_u32_e32 v4, vcc, s38, v54
	s_nop 1
	v_addc_co_u32_e32 v5, vcc, 0, v55, vcc
	s_waitcnt lgkmcnt(0)
	global_store_dwordx4 v[4:5], v[0:3], off nt
	ds_read_b128 v[0:3], v138 offset:6912
	v_add_co_u32_e32 v4, vcc, 0xa8000, v54
	s_nop 1
	v_addc_co_u32_e32 v5, vcc, 0, v55, vcc
	s_waitcnt lgkmcnt(0)
	global_store_dwordx4 v[4:5], v[0:3], off nt
	ds_read_b128 v[0:3], v138 offset:8064
	v_add_co_u32_e32 v4, vcc, 0xb4000, v54
	s_nop 1
	v_addc_co_u32_e32 v5, vcc, 0, v55, vcc
	s_waitcnt lgkmcnt(0)
	global_store_dwordx4 v[4:5], v[0:3], off nt
	s_cbranch_scc0 .LBB0_941

.LBB0_1037:
	s_or_b64 exec, exec, s[38:39]
	s_cmpk_gt_i32 s2, 0x4ff
	s_waitcnt lgkmcnt(0)
	s_barrier
	s_cbranch_scc1 .LBB0_1042
	s_lshr_b32 s98, s2, 3
	s_and_b32 s98, s98, 7
	s_cmp_eq_u32 s98, 0
	s_cbranch_scc1 .Lstag_done_p10

.Lstag_done_p10:
	s_mov_b32 s101, 0
	s_add_i32 s20, 0, 0x240a8
	s_movk_i32 s3, 0x600
	v_mov_b32_e32 v133, s20
	s_mov_b64 s[4:5], 0x2400000
	s_mov_b64 s[6:7], 0x1200000
	s_mov_b32 s21, 0x3ffff0
	v_mov_b32_e32 v129, 0
	s_mov_b32 s22, 0xa000
	s_movk_i32 s23, 0xc000
	s_mov_b64 s[8:9], 0x1200080
	s_mov_b64 s[10:11], 0x2400080
	s_add_i32 s24, 0, 0x10000
	s_add_i32 s25, 0, 0x18000
	s_movk_i32 s26, 0x1400
	s_movk_i32 s27, 0x2400
	s_mov_b64 s[12:13], 0x11400000
	s_mov_b32 s28, 0x14000
	s_mov_b32 s29, 0x1e000
	s_mov_b32 s30, 0x50000
	s_mov_b32 s31, 0x5a000
	s_mov_b32 s34, 0x64000
	s_mov_b32 s35, 0x6e000
	s_mov_b32 s38, 0x78000
	s_mov_b32 s39, 0x82000
	s_mov_b32 s42, s2
.LBB0_1039:
	s_mul_hi_i32 s14, s42, 0x66666667
	s_lshr_b32 s15, s14, 31
	s_ashr_i32 s14, s14, 6
	s_add_i32 s15, s14, s15
	s_mul_i32 s14, s15, 0xa0
	s_sub_i32 s16, s42, s14
	s_sext_i32_i16 s14, s16
	s_bfe_u32 s14, s14, 0x4001b
	s_add_i32 s14, s16, s14
	s_sext_i32_i16 s17, s14
	s_and_b32 s14, s14, 0xfff0
	s_sub_i32 s14, s16, s14
	s_sext_i32_i16 s19, s14
	s_lshl_b32 s14, s17, 4
	s_and_b32 s14, s14, 0xffffff00
	v_mov_b32_e32 v148, v132
	v_mov_b32_e32 v18, v132
	s_cmpk_lt_i32 s16, 0x50
	ds_read_b64 v[0:1], v133
	s_cselect_b32 s16, s3, 0xc00
	v_lshlrev_b32_e32 v9, 4, v18
	v_and_b32_e32 v8, 32, v18
	v_lshrrev_b32_e32 v10, 1, v18
	v_bitop3_b32 v8, v9, v8, 48 bitop3:0x6c
	s_add_i32 s18, s14, s16
	s_lshl_b32 s15, s15, 12
	s_lshl_b32 s16, s19, 8
	v_bfe_u32 v19, v18, 2, 4
	v_and_b32_e32 v20, 32, v10
	v_lshrrev_b32_e32 v21, 1, v8
	v_ashrrev_i32_e32 v22, 3, v18
	s_add_i32 s16, s16, s15
	v_or_b32_e32 v12, v21, v20
	v_and_or_b32 v8, v22, s21, v19
	s_ashr_i32 s17, s16, 31
	v_and_b32_e32 v11, 0xfffffc00, v9
	v_lshl_or_b32 v128, v8, 10, v12
	v_add_u32_e32 v8, 0x2000, v9
	v_add_u32_e32 v10, 0x4000, v9
	v_add_u32_e32 v9, 0x6000, v9
	s_lshl_b64 s[44:45], s[16:17], 11
	s_ashr_i32 s19, s18, 31
	v_ashrrev_i32_e32 v23, 7, v8
	v_ashrrev_i32_e32 v24, 7, v10
	v_ashrrev_i32_e32 v25, 7, v9
	s_waitcnt lgkmcnt(0)
	v_lshl_add_u64 v[2:3], v[0:1], 0, s[44:45]
	s_lshl_b64 s[18:19], s[18:19], 11
	v_and_or_b32 v8, v23, s21, v19
	v_and_or_b32 v10, v24, s21, v19
	v_and_or_b32 v9, v25, s21, v19
	v_add_u32_e32 v149, 0, v11
	v_lshl_add_u64 v[4:5], v[2:3], 0, s[4:5]
	v_lshl_add_u64 v[0:1], v[0:1], 0, s[18:19]
	v_lshl_or_b32 v8, v8, 10, v12
	v_lshl_or_b32 v10, v10, 10, v12
	v_lshl_or_b32 v12, v9, 10, v12
	v_add_u32_e32 v9, 0x8000, v149
	v_lshlrev_b64 v[14:15], 1, v[128:129]
	v_readfirstlane_b32 s15, v149
	v_lshl_add_u64 v[6:7], v[0:1], 0, s[6:7]
	v_lshl_add_u64 v[16:17], v[4:5], 0, v[14:15]
	s_mov_b32 m0, s15
	v_readfirstlane_b32 s15, v9
	v_mov_b32_e32 v9, v129
	v_add_u32_e32 v11, 0x2000, v149
	s_cmp_lg_u32 s101, 0
	s_cbranch_scc1 .Lnxh_1040_7
	global_load_lds_dwordx4 v[16:17], off

.Lnxh_1040_0:
	v_and_b32_e32 v4, 48, v18
	v_lshlrev_b32_e32 v5, 6, v26
	v_and_b32_e32 v6, 32, v6
	v_bitop3_b32 v150, v5, v6, v4 bitop3:0x36
	v_lshlrev_b32_e32 v5, 7, v18
	v_and_b32_e32 v151, 0x6000, v5
	v_lshlrev_b32_e32 v5, 6, v18
	v_and_b32_e32 v152, 0xffffc000, v5
	v_and_b32_e32 v5, 0x3c0, v5
	v_bitop3_b32 v154, v5, v6, v4 bitop3:0x36
	v_lshlrev_b32_e32 v4, 10, v25
	v_and_or_b32 v4, v4, s23, v21
	v_lshlrev_b32_e32 v6, 10, v24
	v_or3_b32 v128, v4, v10, v20
	v_and_or_b32 v6, v6, s23, v21
	v_lshlrev_b32_e32 v8, 10, v23
	v_lshlrev_b64 v[4:5], 1, v[128:129]
	v_or3_b32 v128, v6, v10, v20
	v_and_or_b32 v8, v8, s23, v21
	v_lshlrev_b32_e32 v11, 10, v22
	v_lshlrev_b64 v[6:7], 1, v[128:129]
	v_or3_b32 v128, v8, v10, v20
	v_and_or_b32 v11, v11, s23, v21
	v_lshlrev_b64 v[8:9], 1, v[128:129]
	v_or3_b32 v128, v11, v10, v20
	s_nop 0
	v_lshl_add_u64 v[0:1], v[0:1], 0, s[8:9]
	v_lshlrev_b64 v[10:11], 1, v[128:129]
	v_lshl_add_u64 v[130:131], v[0:1], 0, v[4:5]
	v_lshl_add_u64 v[134:135], v[0:1], 0, v[6:7]
	v_lshl_add_u64 v[136:137], v[0:1], 0, v[8:9]
	v_lshl_add_u64 v[138:139], v[0:1], 0, v[10:11]
	v_lshl_add_u64 v[0:1], v[2:3], 0, s[10:11]
	v_or_b32_e32 v153, 0x800, v152
	v_or_b32_e32 v155, 0x1000, v152
	v_or_b32_e32 v156, 0x1800, v152
	v_or_b32_e32 v157, 0x2000, v152
	v_or_b32_e32 v158, 0x2800, v152
	v_or_b32_e32 v159, 0x3000, v152
	v_or_b32_e32 v160, 0x3800, v152
	v_lshl_add_u64 v[140:141], v[0:1], 0, v[4:5]
	v_lshl_add_u64 v[142:143], v[0:1], 0, v[6:7]
	v_lshl_add_u64 v[144:145], v[0:1], 0, v[8:9]
	v_lshl_add_u64 v[146:147], v[0:1], 0, v[10:11]
	s_mov_b64 s[18:19], 0
	s_mov_b32 s15, 0
	v_mov_b32_e32 v0, 0
	v_mov_b32_e32 v1, v129
	v_mov_b32_e32 v2, v129
	v_mov_b32_e32 v3, v129
	v_mov_b32_e32 v4, 0
	v_mov_b32_e32 v5, v129
	v_mov_b32_e32 v6, v129
	v_mov_b32_e32 v7, v129
	v_mov_b32_e32 v8, 0
	v_mov_b32_e32 v9, v129
	v_mov_b32_e32 v10, v129
	v_mov_b32_e32 v11, v129
	v_mov_b32_e32 v12, 0
	v_mov_b32_e32 v14, v129
	v_mov_b32_e32 v15, v129
	v_mov_b32_e32 v16, 0
	v_mov_b32_e32 v17, v129
	v_mov_b32_e32 v18, v129
	v_mov_b32_e32 v19, v129
	v_mov_b32_e32 v20, 0
	v_mov_b32_e32 v21, v129
	v_mov_b32_e32 v22, v129
	v_mov_b32_e32 v23, v129
	v_mov_b32_e32 v24, 0
	v_mov_b32_e32 v25, v129
	v_mov_b32_e32 v26, v129
	v_mov_b32_e32 v27, v129
	v_mov_b32_e32 v28, 0
	v_mov_b32_e32 v29, v129
	v_mov_b32_e32 v30, v129
	v_mov_b32_e32 v31, v129
	v_mov_b32_e32 v32, 0
	v_mov_b32_e32 v33, v129
	v_mov_b32_e32 v34, v129
	v_mov_b32_e32 v35, v129
	v_mov_b32_e32 v36, 0
	v_mov_b32_e32 v37, v129
	v_mov_b32_e32 v38, v129
	v_mov_b32_e32 v39, v129
	v_mov_b32_e32 v40, 0
	v_mov_b32_e32 v41, v129
	v_mov_b32_e32 v42, v129
	v_mov_b32_e32 v43, v129
	v_mov_b32_e32 v44, 0
	v_mov_b32_e32 v45, v129
	v_mov_b32_e32 v46, v129
	v_mov_b32_e32 v47, v129
	v_mov_b32_e32 v48, 0
	v_mov_b32_e32 v49, v129
	v_mov_b32_e32 v50, v129
	v_mov_b32_e32 v51, v129
	v_mov_b32_e32 v52, 0
	v_mov_b32_e32 v53, v129
	v_mov_b32_e32 v54, v129
	v_mov_b32_e32 v55, v129
	v_mov_b32_e32 v56, 0
	v_mov_b32_e32 v57, v129
	v_mov_b32_e32 v58, v129
	v_mov_b32_e32 v59, v129
	v_mov_b32_e32 v60, 0
	v_mov_b32_e32 v61, v129
	v_mov_b32_e32 v62, v129
	v_mov_b32_e32 v63, v129
	v_mov_b32_e32 v64, 0
	v_mov_b32_e32 v65, v129
	v_mov_b32_e32 v66, v129
	v_mov_b32_e32 v67, v129
	v_mov_b32_e32 v68, 0
	v_mov_b32_e32 v69, v129
	v_mov_b32_e32 v70, v129
	v_mov_b32_e32 v71, v129
	v_mov_b32_e32 v72, 0
	v_mov_b32_e32 v73, v129
	v_mov_b32_e32 v74, v129
	v_mov_b32_e32 v75, v129
	v_mov_b32_e32 v76, 0
	v_mov_b32_e32 v77, v129
	v_mov_b32_e32 v78, v129
	v_mov_b32_e32 v79, v129
	v_mov_b32_e32 v80, 0
	v_mov_b32_e32 v81, v129
	v_mov_b32_e32 v82, v129
	v_mov_b32_e32 v83, v129
	v_mov_b32_e32 v84, 0
	v_mov_b32_e32 v85, v129
	v_mov_b32_e32 v86, v129
	v_mov_b32_e32 v87, v129
	v_mov_b32_e32 v88, 0
	v_mov_b32_e32 v89, v129
	v_mov_b32_e32 v90, v129
	v_mov_b32_e32 v91, v129
	v_mov_b32_e32 v92, 0
	v_mov_b32_e32 v93, v129
	v_mov_b32_e32 v94, v129
	v_mov_b32_e32 v95, v129
	v_mov_b32_e32 v96, 0
	v_mov_b32_e32 v97, v129
	v_mov_b32_e32 v98, v129
	v_mov_b32_e32 v99, v129
	v_mov_b32_e32 v100, 0
	v_mov_b32_e32 v101, v129
	v_mov_b32_e32 v102, v129
	v_mov_b32_e32 v103, v129
	v_mov_b32_e32 v104, 0
	v_mov_b32_e32 v105, v129
	v_mov_b32_e32 v106, v129
	v_mov_b32_e32 v107, v129
	v_mov_b32_e32 v108, 0
	v_mov_b32_e32 v109, v129
	v_mov_b32_e32 v110, v129
	v_mov_b32_e32 v111, v129
	v_mov_b32_e32 v112, 0
	v_mov_b32_e32 v113, v129
	v_mov_b32_e32 v114, v129
	v_mov_b32_e32 v115, v129
	v_mov_b32_e32 v116, 0
	v_mov_b32_e32 v117, v129
	v_mov_b32_e32 v118, v129
	v_mov_b32_e32 v119, v129
	v_mov_b32_e32 v120, 0
	v_mov_b32_e32 v121, v129
	v_mov_b32_e32 v122, v129
	v_mov_b32_e32 v123, v129
	v_mov_b32_e32 v124, 0
	v_mov_b32_e32 v125, v129
	v_mov_b32_e32 v126, v129
	v_mov_b32_e32 v127, v129
	s_cmp_lg_u32 s101, 0
	s_cbranch_scc1 .Lnxw_1040
	s_waitcnt vmcnt(0)
.Lnxw_1040:
	s_waitcnt vmcnt(16) lgkmcnt(0)
	s_barrier
	v_readfirstlane_b32 s100, v149
	s_mov_b64 s[98:99], 0x80
	s_and_b32 s17, s15, 0x10000
	s_xor_b32 s43, s17, 0x10000
	s_add_i32 s17, s17, 0
	v_add3_u32 v128, s17, v150, v151
	v_add3_u32 v161, s17, v150, v152
	v_add3_u32 v194, s17, v154, v153
	v_add3_u32 v195, s17, v154, v155
	v_add3_u32 v196, s17, v154, v156
	v_add3_u32 v197, s17, v154, v157
	v_add3_u32 v198, s17, v154, v158
	v_add3_u32 v199, s17, v154, v159
	v_add3_u32 v200, s17, v154, v160
	ds_read_b128 v[178:181], v128 offset:32768
	ds_read_b128 v[162:165], v161
	ds_read_b128 v[166:169], v194
	ds_read_b128 v[170:173], v195
	ds_read_b128 v[174:177], v196
	ds_read_b128 v[182:185], v128 offset:34816
	ds_read_b128 v[186:189], v128 offset:36864
	ds_read_b128 v[190:193], v128 offset:38912
	s_add_i32 s101, s100, s43
	s_mov_b32 m0, s101
	s_nop 0
	global_load_lds_dwordx4 v[146:147], off
	s_add_i32 m0, s101, 0x8000
	s_nop 0
	global_load_lds_dwordx4 v[138:139], off
	s_add_i32 m0, s101, 0x2000
	s_nop 0
	global_load_lds_dwordx4 v[144:145], off
	s_add_i32 m0, s101, 0xa000
	s_nop 0
	global_load_lds_dwordx4 v[136:137], off
	s_add_i32 m0, s101, 0x4000
	s_nop 0
	global_load_lds_dwordx4 v[142:143], off
	s_add_i32 m0, s101, 0xc000
	s_nop 0
	global_load_lds_dwordx4 v[134:135], off
	s_add_i32 m0, s101, 0x6000
	s_nop 0
	global_load_lds_dwordx4 v[140:141], off
	s_add_i32 m0, s101, 0xe000
	s_nop 0
	global_load_lds_dwordx4 v[130:131], off

.Lex_1040:
	s_mov_b32 s101, 0
	s_cmpk_lg_i32 s40, 0x100
	s_cbranch_scc1 .Lnxn_1040
	s_add_i32 s98, s42, s40
	s_cmpk_gt_i32 s98, 0x4ff
	s_cbranch_scc1 .Lnxn_1040
	s_mul_hi_u32 s98, s42, 0x33333334
	s_lshr_b32 s98, s98, 5
	s_mul_i32 s98, s98, 0xa0
	s_sub_i32 s98, s42, s98
	s_lshr_b32 s98, s98, 4
	s_mov_b32 vcc_lo, 0
	s_mov_b32 s99, 0
	s_cmpk_lg_u32 s98, 0
	s_cbranch_scc1 .Lnxj_1040_0
	s_mov_b32 vcc_lo, 0x5ff880
	s_mov_b32 s99, 0x7ff880
.Lnxj_1040_0:
	s_cmpk_lg_u32 s98, 1
	s_cbranch_scc1 .Lnxj_1040_1
	s_mov_b32 vcc_lo, 0x5ff880
	s_mov_b32 s99, 0x7ff880
.Lnxj_1040_1:
	s_cmpk_lg_u32 s98, 2
	s_cbranch_scc1 .Lnxj_1040_2
	s_mov_b32 vcc_lo, 0x5ff880
	s_mov_b32 s99, 0x7ff880
.Lnxj_1040_2:
	s_cmpk_lg_u32 s98, 3
	s_cbranch_scc1 .Lnxj_1040_3
	s_mov_b32 vcc_lo, 0x5ff880
	s_mov_b32 s99, 0x7ff880
.Lnxj_1040_3:
	s_cmpk_lg_u32 s98, 4
	s_cbranch_scc1 .Lnxj_1040_4
	s_mov_b32 vcc_lo, 0xffdff880
	s_mov_b32 s99, 0xfff880
.Lnxj_1040_4:
	s_cmpk_lg_u32 s98, 5
	s_cbranch_scc1 .Lnxj_1040_5
	s_mov_b32 vcc_lo, 0xffaff880
	s_mov_b32 s99, 0xfff880
.Lnxj_1040_5:
	s_cmpk_lg_u32 s98, 6
	s_cbranch_scc1 .Lnxj_1040_6
	s_mov_b32 vcc_lo, 0xffaff880
	s_mov_b32 s99, 0xfff880
.Lnxj_1040_6:
	s_cmpk_lg_u32 s98, 7
	s_cbranch_scc1 .Lnxj_1040_7
	s_mov_b32 vcc_lo, 0xffaff880
	s_mov_b32 s99, 0xfff880
.Lnxj_1040_7:
	s_cmpk_lg_u32 s98, 8
	s_cbranch_scc1 .Lnxj_1040_8
	s_mov_b32 vcc_lo, 0xffaff880
	s_mov_b32 s99, 0xfff880
.Lnxj_1040_8:
	s_cmpk_lg_u32 s98, 9
	s_cbranch_scc1 .Lnxj_1040_9
	s_mov_b32 vcc_lo, 0xffdff880
	s_mov_b32 s99, 0xfff880

.Lnxn_1040:
	s_waitcnt lgkmcnt(0)
	v_add3_u32 v128, s24, v154, v160
	v_add3_u32 v130, s24, v154, v159
	v_add3_u32 v131, s24, v154, v158
	v_add3_u32 v146, s24, v154, v157
	v_add3_u32 v147, s24, v154, v156
	v_add3_u32 v149, s24, v154, v155
	v_add3_u32 v186, s24, v154, v153
	v_add3_u32 v187, s24, v150, v152
	v_add3_u32 v188, s25, v150, v151
	ds_read_b128 v[134:137], v128
	ds_read_b128 v[138:141], v130
	ds_read_b128 v[142:145], v131
	ds_read_b128 v[158:161], v146
	ds_read_b128 v[162:165], v147
	ds_read_b128 v[166:169], v149
	ds_read_b128 v[154:157], v186
	ds_read_b128 v[170:173], v187
	ds_read_b128 v[178:181], v188 offset:4096
	s_waitcnt lgkmcnt(0)
	v_mfma_f32_16x16x32_bf16 v[4:7], v[178:181], v[138:141], v[4:7]
	ds_read_b128 v[174:177], v188 offset:2048
	s_waitcnt lgkmcnt(0)
	v_mfma_f32_16x16x32_bf16 v[8:11], v[174:177], v[138:141], v[8:11]
	ds_read_b128 v[150:153], v188
	s_waitcnt lgkmcnt(0)
	v_mfma_f32_16x16x32_bf16 v[12:15], v[150:153], v[138:141], v[12:15]
	v_mfma_f32_16x16x32_bf16 v[112:115], v[150:153], v[134:137], v[112:115]
	v_mfma_f32_16x16x32_bf16 v[108:111], v[150:153], v[170:173], v[108:111]
	v_mfma_f32_16x16x32_bf16 v[92:95], v[150:153], v[154:157], v[92:95]
	v_mfma_f32_16x16x32_bf16 v[76:79], v[150:153], v[166:169], v[76:79]
	v_mfma_f32_16x16x32_bf16 v[116:119], v[174:177], v[134:137], v[116:119]
	v_mfma_f32_16x16x32_bf16 v[104:107], v[174:177], v[170:173], v[104:107]
	v_mfma_f32_16x16x32_bf16 v[88:91], v[174:177], v[154:157], v[88:91]
	v_mfma_f32_16x16x32_bf16 v[72:75], v[174:177], v[166:169], v[72:75]
	v_mfma_f32_16x16x32_bf16 v[120:123], v[178:181], v[134:137], v[120:123]
	v_mfma_f32_16x16x32_bf16 v[100:103], v[178:181], v[170:173], v[100:103]
	v_mfma_f32_16x16x32_bf16 v[84:87], v[178:181], v[154:157], v[84:87]
	v_mfma_f32_16x16x32_bf16 v[68:71], v[178:181], v[166:169], v[68:71]
	ds_read_b128 v[182:185], v188 offset:6144
	s_waitcnt lgkmcnt(0)
	v_mfma_f32_16x16x32_bf16 v[124:127], v[182:185], v[134:137], v[124:127]
	v_mfma_f32_16x16x32_bf16 v[96:99], v[182:185], v[170:173], v[96:99]
	v_mfma_f32_16x16x32_bf16 v[80:83], v[182:185], v[154:157], v[80:83]
	v_mfma_f32_16x16x32_bf16 v[64:67], v[182:185], v[166:169], v[64:67]
	v_mfma_f32_16x16x32_bf16 v[48:51], v[182:185], v[162:165], v[48:51]
	v_mfma_f32_16x16x32_bf16 v[52:55], v[178:181], v[162:165], v[52:55]
	v_mfma_f32_16x16x32_bf16 v[56:59], v[174:177], v[162:165], v[56:59]
	v_mfma_f32_16x16x32_bf16 v[60:63], v[150:153], v[162:165], v[60:63]
	v_mfma_f32_16x16x32_bf16 v[44:47], v[150:153], v[158:161], v[44:47]
	v_mfma_f32_16x16x32_bf16 v[40:43], v[174:177], v[158:161], v[40:43]
	v_mfma_f32_16x16x32_bf16 v[36:39], v[178:181], v[158:161], v[36:39]
	v_mfma_f32_16x16x32_bf16 v[32:35], v[182:185], v[158:161], v[32:35]
	v_mfma_f32_16x16x32_bf16 v[28:31], v[150:153], v[142:145], v[28:31]
	v_mfma_f32_16x16x32_bf16 v[24:27], v[174:177], v[142:145], v[24:27]
	v_mfma_f32_16x16x32_bf16 v[20:23], v[178:181], v[142:145], v[20:23]
	v_mfma_f32_16x16x32_bf16 v[16:19], v[182:185], v[142:145], v[16:19]
	v_mfma_f32_16x16x32_bf16 v[0:3], v[182:185], v[138:141], v[0:3]
	ds_read_b128 v[134:137], v188 offset:1024
	ds_read_b128 v[138:141], v188 offset:3072
	ds_read_b128 v[142:145], v188 offset:5120
	ds_read_b128 v[154:157], v188 offset:7168
	ds_read_b128 v[150:153], v187 offset:1024
	ds_read_b128 v[158:161], v186 offset:1024
	ds_read_b128 v[162:165], v149 offset:1024
	ds_read_b128 v[166:169], v147 offset:1024
	s_waitcnt lgkmcnt(3)
	v_mfma_f32_16x16x32_bf16 v[108:111], v[134:137], v[150:153], v[108:111]
	v_mfma_f32_16x16x32_bf16 v[104:107], v[138:141], v[150:153], v[104:107]
	v_mfma_f32_16x16x32_bf16 v[100:103], v[142:145], v[150:153], v[100:103]
	v_mfma_f32_16x16x32_bf16 v[96:99], v[154:157], v[150:153], v[96:99]
	ds_read_b128 v[150:153], v146 offset:1024
	s_waitcnt lgkmcnt(3)
	v_mfma_f32_16x16x32_bf16 v[92:95], v[134:137], v[158:161], v[92:95]
	v_mfma_f32_16x16x32_bf16 v[88:91], v[138:141], v[158:161], v[88:91]
	v_mfma_f32_16x16x32_bf16 v[84:87], v[142:145], v[158:161], v[84:87]
	v_mfma_f32_16x16x32_bf16 v[80:83], v[154:157], v[158:161], v[80:83]
	ds_read_b128 v[158:161], v131 offset:1024
	s_waitcnt lgkmcnt(3)
	v_mfma_f32_16x16x32_bf16 v[76:79], v[134:137], v[162:165], v[76:79]
	v_mfma_f32_16x16x32_bf16 v[72:75], v[138:141], v[162:165], v[72:75]
	v_mfma_f32_16x16x32_bf16 v[68:71], v[142:145], v[162:165], v[68:71]
	v_mfma_f32_16x16x32_bf16 v[64:67], v[154:157], v[162:165], v[64:67]
	ds_read_b128 v[162:165], v130 offset:1024
	s_waitcnt lgkmcnt(3)
	v_mfma_f32_16x16x32_bf16 v[60:63], v[134:137], v[166:169], v[60:63]
	v_mfma_f32_16x16x32_bf16 v[56:59], v[138:141], v[166:169], v[56:59]
	v_mfma_f32_16x16x32_bf16 v[52:55], v[142:145], v[166:169], v[52:55]
	v_mfma_f32_16x16x32_bf16 v[48:51], v[154:157], v[166:169], v[48:51]
	ds_read_b128 v[166:169], v128 offset:1024
	s_waitcnt lgkmcnt(3)
	v_mfma_f32_16x16x32_bf16 v[44:47], v[134:137], v[150:153], v[44:47]
	v_mfma_f32_16x16x32_bf16 v[40:43], v[138:141], v[150:153], v[40:43]
	v_mfma_f32_16x16x32_bf16 v[36:39], v[142:145], v[150:153], v[36:39]
	v_mfma_f32_16x16x32_bf16 v[32:35], v[154:157], v[150:153], v[32:35]
	s_waitcnt lgkmcnt(2)
	v_mfma_f32_16x16x32_bf16 v[28:31], v[134:137], v[158:161], v[28:31]
	v_mfma_f32_16x16x32_bf16 v[24:27], v[138:141], v[158:161], v[24:27]
	v_mfma_f32_16x16x32_bf16 v[20:23], v[142:145], v[158:161], v[20:23]
	v_mfma_f32_16x16x32_bf16 v[16:19], v[154:157], v[158:161], v[16:19]
	s_waitcnt lgkmcnt(1)
	v_mfma_f32_16x16x32_bf16 v[12:15], v[134:137], v[162:165], v[12:15]
	v_mfma_f32_16x16x32_bf16 v[8:11], v[138:141], v[162:165], v[8:11]
	v_mfma_f32_16x16x32_bf16 v[4:7], v[142:145], v[162:165], v[4:7]
	v_mfma_f32_16x16x32_bf16 v[0:3], v[154:157], v[162:165], v[0:3]
	s_waitcnt lgkmcnt(0)
	v_mfma_f32_16x16x32_bf16 v[112:115], v[134:137], v[166:169], v[112:115]
	v_mfma_f32_16x16x32_bf16 v[116:119], v[138:141], v[166:169], v[116:119]
	v_mfma_f32_16x16x32_bf16 v[120:123], v[142:145], v[166:169], v[120:123]
	v_mfma_f32_16x16x32_bf16 v[124:127], v[154:157], v[166:169], v[124:127]
	v_mov_b32_e32 v128, s20
	s_waitcnt vmcnt(8)
	s_barrier
	ds_read_b64 v[130:131], v128
	v_ashrrev_i32_e32 v128, 1, v148
	v_and_b32_e32 v128, 0xffffff80, v128
	v_add_u32_e32 v128, s16, v128
	s_ashr_i32 s15, s14, 31
	s_waitcnt lgkmcnt(0)
	v_mad_i64_i32 v[130:131], s[16:17], v128, s26, v[130:131]
	v_and_b32_e32 v128, 0xc0, v148
	v_lshrrev_b32_e32 v135, 6, v148
	v_lshl_add_u64 v[130:131], s[14:15], 1, v[130:131]
	v_lshlrev_b32_e32 v128, 1, v128
	v_lshl_add_u64 v[130:131], v[130:131], 0, v[128:129]
	v_mul_lo_u32 v128, v135, s27
	v_add_u32_e32 v135, s24, v128
	v_lshrrev_b32_e32 v128, 1, v148
	v_and_b32_e32 v136, 24, v128
	v_lshlrev_b32_e32 v128, 4, v148
	v_bfe_u32 v137, v148, 3, 3
	v_and_b32_e32 v134, 15, v148
	v_and_b32_e32 v128, 0x70, v128
	v_mul_u32_u24_e32 v138, 0x90, v137
	v_lshl_add_u64 v[130:131], v[130:131], 0, v[128:129]
	v_add3_u32 v138, v135, v128, v138
	v_mul_u32_u24_e32 v128, 0x90, v134
	v_add3_u32 v134, v135, v136, v128
	v_cvt_pk_bf16_f32 v108, v108, v109
	v_cvt_pk_bf16_f32 v109, v110, v111
	v_cvt_pk_bf16_f32 v104, v104, v105
	v_cvt_pk_bf16_f32 v105, v106, v107
	v_cvt_pk_bf16_f32 v100, v100, v101
	v_cvt_pk_bf16_f32 v101, v102, v103
	v_cvt_pk_bf16_f32 v96, v96, v97
	v_cvt_pk_bf16_f32 v97, v98, v99
	v_cvt_pk_bf16_f32 v92, v92, v93
	v_cvt_pk_bf16_f32 v93, v94, v95
	v_cvt_pk_bf16_f32 v88, v88, v89
	v_cvt_pk_bf16_f32 v89, v90, v91
	v_cvt_pk_bf16_f32 v84, v84, v85
	v_cvt_pk_bf16_f32 v85, v86, v87
	v_cvt_pk_bf16_f32 v80, v80, v81
	v_cvt_pk_bf16_f32 v81, v82, v83
	v_cvt_pk_bf16_f32 v76, v76, v77
	v_cvt_pk_bf16_f32 v77, v78, v79
	v_cvt_pk_bf16_f32 v72, v72, v73
	v_cvt_pk_bf16_f32 v73, v74, v75
	v_cvt_pk_bf16_f32 v68, v68, v69
	v_cvt_pk_bf16_f32 v69, v70, v71
	v_cvt_pk_bf16_f32 v64, v64, v65
	v_cvt_pk_bf16_f32 v65, v66, v67
	v_cvt_pk_bf16_f32 v60, v60, v61
	v_cvt_pk_bf16_f32 v61, v62, v63
	v_cvt_pk_bf16_f32 v56, v56, v57
	v_cvt_pk_bf16_f32 v57, v58, v59
	v_cvt_pk_bf16_f32 v52, v52, v53
	v_cvt_pk_bf16_f32 v53, v54, v55
	v_cvt_pk_bf16_f32 v48, v48, v49
	v_cvt_pk_bf16_f32 v49, v50, v51
	ds_write_b64 v134, v[108:109]
	ds_write_b64 v134, v[104:105] offset:32
	ds_write_b64 v134, v[100:101] offset:64
	ds_write_b64 v134, v[96:97] offset:96
	ds_write_b64 v134, v[92:93] offset:2304
	ds_write_b64 v134, v[88:89] offset:2336
	ds_write_b64 v134, v[84:85] offset:2368
	ds_write_b64 v134, v[80:81] offset:2400
	ds_write_b64 v134, v[76:77] offset:4608
	ds_write_b64 v134, v[72:73] offset:4640
	ds_write_b64 v134, v[68:69] offset:4672
	ds_write_b64 v134, v[64:65] offset:4704
	ds_write_b64 v134, v[60:61] offset:6912
	ds_write_b64 v134, v[56:57] offset:6944
	ds_write_b64 v134, v[52:53] offset:6976
	ds_write_b64 v134, v[48:49] offset:7008
	ds_read_b128 v[48:51], v138
	v_mul_u32_u24_e32 v54, 0xa00, v137
	v_lshl_add_u64 v[52:53], v[130:131], 0, s[12:13]
	v_lshlrev_b32_e32 v128, 1, v54
	v_lshl_add_u64 v[54:55], v[52:53], 0, v[128:129]
	s_waitcnt lgkmcnt(0)
	global_store_dwordx4 v[54:55], v[48:51], off nt
	ds_read_b128 v[48:51], v138 offset:1152
	v_add_co_u32_e32 v56, vcc, s22, v54
	v_cvt_pk_bf16_f32 v0, v0, v1
	s_nop 0
	v_addc_co_u32_e32 v57, vcc, 0, v55, vcc
	s_waitcnt lgkmcnt(0)
	global_store_dwordx4 v[56:57], v[48:51], off nt
	ds_read_b128 v[48:51], v138 offset:2304
	v_add_co_u32_e32 v56, vcc, s28, v54
	v_cvt_pk_bf16_f32 v1, v2, v3
	s_nop 0
	v_addc_co_u32_e32 v57, vcc, 0, v55, vcc
	s_waitcnt lgkmcnt(0)
	global_store_dwordx4 v[56:57], v[48:51], off nt
	ds_read_b128 v[48:51], v138 offset:3456
	v_add_co_u32_e32 v56, vcc, s29, v54
	v_cvt_pk_bf16_f32 v44, v44, v45
	s_nop 0
	v_addc_co_u32_e32 v57, vcc, 0, v55, vcc
	s_waitcnt lgkmcnt(0)
	global_store_dwordx4 v[56:57], v[48:51], off nt
	ds_read_b128 v[48:51], v138 offset:4608
	v_add_u32_e32 v56, 0x28000, v128
	v_mov_b32_e32 v57, v129
	v_lshl_add_u64 v[56:57], v[52:53], 0, v[56:57]
	v_cvt_pk_bf16_f32 v45, v46, v47
	s_waitcnt lgkmcnt(0)
	global_store_dwordx4 v[56:57], v[48:51], off nt
	ds_read_b128 v[48:51], v138 offset:5760
	v_add_u32_e32 v56, 0x32000, v128
	v_mov_b32_e32 v57, v129
	v_lshl_add_u64 v[56:57], v[52:53], 0, v[56:57]
	v_cvt_pk_bf16_f32 v40, v40, v41
	s_waitcnt lgkmcnt(0)
	global_store_dwordx4 v[56:57], v[48:51], off nt
	ds_read_b128 v[48:51], v138 offset:6912
	v_add_u32_e32 v56, 0x3c000, v128
	v_mov_b32_e32 v57, v129
	v_lshl_add_u64 v[56:57], v[52:53], 0, v[56:57]
	v_add_u32_e32 v128, 0x46000, v128
	s_waitcnt lgkmcnt(0)
	global_store_dwordx4 v[56:57], v[48:51], off nt
	ds_read_b128 v[48:51], v138 offset:8064
	v_lshl_add_u64 v[52:53], v[52:53], 0, v[128:129]
	v_cvt_pk_bf16_f32 v41, v42, v43
	v_cvt_pk_bf16_f32 v36, v36, v37
	v_cvt_pk_bf16_f32 v37, v38, v39
	s_waitcnt lgkmcnt(0)
	global_store_dwordx4 v[52:53], v[48:51], off nt
	ds_write_b64 v134, v[0:1] offset:4704
	v_cvt_pk_bf16_f32 v0, v112, v113
	v_cvt_pk_bf16_f32 v1, v114, v115
	ds_write_b64 v134, v[0:1] offset:6912
	v_cvt_pk_bf16_f32 v0, v116, v117
	v_cvt_pk_bf16_f32 v1, v118, v119
	ds_write_b64 v134, v[0:1] offset:6944
	v_cvt_pk_bf16_f32 v0, v120, v121
	v_cvt_pk_bf16_f32 v1, v122, v123
	v_cvt_pk_bf16_f32 v32, v32, v33
	v_cvt_pk_bf16_f32 v33, v34, v35
	v_cvt_pk_bf16_f32 v28, v28, v29
	v_cvt_pk_bf16_f32 v29, v30, v31
	v_cvt_pk_bf16_f32 v24, v24, v25
	v_cvt_pk_bf16_f32 v25, v26, v27
	v_cvt_pk_bf16_f32 v20, v20, v21
	v_cvt_pk_bf16_f32 v21, v22, v23
	v_cvt_pk_bf16_f32 v16, v16, v17
	v_cvt_pk_bf16_f32 v17, v18, v19
	v_cvt_pk_bf16_f32 v12, v12, v13
	v_cvt_pk_bf16_f32 v13, v14, v15
	v_cvt_pk_bf16_f32 v8, v8, v9
	v_cvt_pk_bf16_f32 v9, v10, v11
	v_cvt_pk_bf16_f32 v4, v4, v5
	v_cvt_pk_bf16_f32 v5, v6, v7
	ds_write_b64 v134, v[0:1] offset:6976
	v_cvt_pk_bf16_f32 v0, v124, v125
	v_cvt_pk_bf16_f32 v1, v126, v127
	ds_write_b64 v134, v[44:45]
	ds_write_b64 v134, v[40:41] offset:32
	ds_write_b64 v134, v[36:37] offset:64
	ds_write_b64 v134, v[32:33] offset:96
	ds_write_b64 v134, v[28:29] offset:2304
	ds_write_b64 v134, v[24:25] offset:2336
	ds_write_b64 v134, v[20:21] offset:2368
	ds_write_b64 v134, v[16:17] offset:2400
	ds_write_b64 v134, v[12:13] offset:4608
	ds_write_b64 v134, v[8:9] offset:4640
	ds_write_b64 v134, v[4:5] offset:4672
	ds_write_b64 v134, v[0:1] offset:7008
	ds_read_b128 v[0:3], v138
	v_add_co_u32_e32 v4, vcc, s30, v54
	s_add_i32 s42, s42, s40
	s_nop 0
	v_addc_co_u32_e32 v5, vcc, 0, v55, vcc
	s_waitcnt lgkmcnt(0)
	global_store_dwordx4 v[4:5], v[0:3], off nt
	ds_read_b128 v[0:3], v138 offset:1152
	v_add_co_u32_e32 v4, vcc, s31, v54
	s_cmpk_gt_i32 s42, 0x4ff
	s_nop 0
	v_addc_co_u32_e32 v5, vcc, 0, v55, vcc
	s_waitcnt lgkmcnt(0)
	global_store_dwordx4 v[4:5], v[0:3], off nt
	ds_read_b128 v[0:3], v138 offset:2304
	v_add_co_u32_e32 v4, vcc, s34, v54
	s_nop 1
	v_addc_co_u32_e32 v5, vcc, 0, v55, vcc
	s_waitcnt lgkmcnt(0)
	global_store_dwordx4 v[4:5], v[0:3], off nt
	ds_read_b128 v[0:3], v138 offset:3456
	v_add_co_u32_e32 v4, vcc, s35, v54
	s_nop 1
	v_addc_co_u32_e32 v5, vcc, 0, v55, vcc
	s_waitcnt lgkmcnt(0)
	global_store_dwordx4 v[4:5], v[0:3], off nt
	ds_read_b128 v[0:3], v138 offset:4608
	v_add_co_u32_e32 v4, vcc, s38, v54
	s_nop 1
	v_addc_co_u32_e32 v5, vcc, 0, v55, vcc
	s_waitcnt lgkmcnt(0)
	global_store_dwordx4 v[4:5], v[0:3], off nt
	ds_read_b128 v[0:3], v138 offset:5760
	v_add_co_u32_e32 v4, vcc, s39, v54
	s_nop 1
	v_addc_co_u32_e32 v5, vcc, 0, v55, vcc
	s_waitcnt lgkmcnt(0)
	global_store_dwordx4 v[4:5], v[0:3], off nt
	ds_read_b128 v[0:3], v138 offset:6912
	v_add_co_u32_e32 v4, vcc, 0x8c000, v54
	s_nop 1
	v_addc_co_u32_e32 v5, vcc, 0, v55, vcc
	s_waitcnt lgkmcnt(0)
	global_store_dwordx4 v[4:5], v[0:3], off nt
	ds_read_b128 v[0:3], v138 offset:8064
	v_add_co_u32_e32 v4, vcc, 0x96000, v54
	s_nop 1
	v_addc_co_u32_e32 v5, vcc, 0, v55, vcc
	s_waitcnt lgkmcnt(0)
	global_store_dwordx4 v[4:5], v[0:3], off nt
	s_cbranch_scc0 .LBB0_1039
